# delta recurrence producer: adjacent-token KDT values paired via DPP into ds_write_b32 (8 LDS writes per chunk instead of 16 ds_write_b16)
# speedup vs baseline: 1.0088x; 1.0052x over previous
; #define LAS __attribute__((address_space(3)))
; __device__ __forceinline__ unsigned f2bf(float f) { return pk2(f, f) & 0xffffu; }
; __device__ __forceinline__ void unpack8(const u32x4 u, float* x) { x[0] = bflo(u.x); x[1] = bfhi(u.x); x[2] = bflo(u.y); x[3] = bfhi(u.y); x[4] = bflo(u.z); x[5] = bfhi(u.z); x[6] = bflo(u.w); x[7] = bfhi(u.w); }
; __device__ __forceinline__ int perm16(int e) { return (e & ~12) | ((e >> 1) & 4) | ((e << 1) & 8); }
; __device__ __forceinline__ void delta_rec_stage(LAS unsigned char* buf, int pt, const DeltaPre& dp) {
;     const int tt = pt >> 3, dg = pt & 7, d0 = dg * 16;
;     { LAS bf16* dst = (LAS bf16*)(buf + (pt < 128 ? DR_TI : DR_AT)) + ((pt & 127) >> 2) * 40 + (pt & 3) * 8; *(LAS u32x4*)dst = dp.tia; }
;     if (pt == 0) *(LAS float*)(buf + DR_EGL) = __expf(dp.gl);
;     const float eg = __expf(dp.gct), ekd = __expf(dp.gl - dp.gct);
;     const float fq = dp.nq * eg, fkb = dp.nk * dp.bet * eg, fkd = dp.nk * ekd, bet = dp.bet;
;     float k[16], q[16], v[16];
;     unpack8(dp.k0, k); unpack8(dp.k1, k + 8); unpack8(dp.q0, q); unpack8(dp.q1, q + 8); unpack8(dp.v0, v); unpack8(dp.v1, v + 8);
;     LAS bf16* KB = (LAS bf16*)(buf + DR_KB) + tt * 136 + d0; LAS bf16* QD = (LAS bf16*)(buf + DR_QD) + tt * 136 + d0;
;     *(LAS bf16x8*)KB = pack8(k[0] * fkb, k[1] * fkb, k[2] * fkb, k[3] * fkb, k[8] * fkb, k[9] * fkb, k[10] * fkb, k[11] * fkb);
;     *(LAS bf16x8*)(KB + 8) = pack8(k[4] * fkb, k[5] * fkb, k[6] * fkb, k[7] * fkb, k[12] * fkb, k[13] * fkb, k[14] * fkb, k[15] * fkb);
;     *(LAS bf16x8*)QD = pack8(q[0] * fq, q[1] * fq, q[2] * fq, q[3] * fq, q[8] * fq, q[9] * fq, q[10] * fq, q[11] * fq);
;     *(LAS bf16x8*)(QD + 8) = pack8(q[4] * fq, q[5] * fq, q[6] * fq, q[7] * fq, q[12] * fq, q[13] * fq, q[14] * fq, q[15] * fq);
;     LAS bf16* KDT = (LAS bf16*)(buf + DR_KDT) + d0 * 40 + perm16(tt);
; #pragma unroll
;     for (int e = 0; e < 16; ++e) KDT[e * 40] = (bf16)f2bf(k[e] * fkd);
;     LAS float* VB = (LAS float*)(buf + DR_VB) + tt * 132 + d0;
; #pragma unroll
;     for (int e4 = 0; e4 < 4; ++e4) *(LAS f32x4*)(VB + 4 * e4) = (f32x4){v[4 * e4] * bet, v[4 * e4 + 1] * bet, v[4 * e4 + 2] * bet, v[4 * e4 + 3] * bet};
; }
.LBB0_1837:
	s_or_b64 exec, exec, s[18:19]
	v_lshrrev_b32_e32 v33, 1, v22
	v_and_b32_e32 v128, 4, v33
	v_lshlrev_b32_e32 v33, 1, v22
	v_and_b32_e32 v129, 8, v33
	v_mul_f32_e32 v33, 0x3fb8aa3b, v117
	v_sub_f32_e32 v34, v118, v117
	v_exp_f32_e32 v33, v33
	v_mul_f32_e32 v34, 0x3fb8aa3b, v34
	v_exp_f32_e32 v34, v34
	s_movk_i32 s18, 0x88
	v_mul_f32_e32 v35, v119, v110
	v_mul_lo_u32 v32, v22, s18
	v_mul_f32_e32 v42, v35, v33
	v_lshlrev_b32_e32 v52, 16, v84
	v_and_b32_e32 v53, 0xffff0000, v84
	v_lshlrev_b32_e32 v54, 16, v85
	v_and_b32_e32 v55, 0xffff0000, v85
	v_lshlrev_b32_e32 v56, 16, v80
	v_and_b32_e32 v57, 0xffff0000, v80
	v_lshlrev_b32_e32 v60, 16, v81
	v_and_b32_e32 v61, 0xffff0000, v81
	v_mul_f32_e32 v40, v120, v33
	v_mul_f32_e32 v117, v119, v34
	v_lshlrev_b32_e32 v91, 1, v32
	v_pk_mul_f32 v[32:33], v[42:43], v[52:53] op_sel_hi:[0,1]
	v_pk_mul_f32 v[34:35], v[42:43], v[54:55] op_sel_hi:[0,1]
	v_pk_mul_f32 v[58:59], v[42:43], v[56:57] op_sel_hi:[0,1]
	v_pk_mul_f32 v[62:63], v[42:43], v[60:61] op_sel_hi:[0,1]
	v_add3_u32 v118, 0, v91, v114
	v_cvt_pk_bf16_f32 v32, v32, v33
	v_cvt_pk_bf16_f32 v33, v34, v35
	v_cvt_pk_bf16_f32 v34, v58, v59
	v_cvt_pk_bf16_f32 v35, v62, v63
	v_lshlrev_b32_e32 v58, 16, v86
	v_and_b32_e32 v59, 0xffff0000, v86
	v_lshlrev_b32_e32 v62, 16, v87
	v_and_b32_e32 v63, 0xffff0000, v87
	v_lshlrev_b32_e32 v84, 16, v82
	v_and_b32_e32 v85, 0xffff0000, v82
	v_lshlrev_b32_e32 v86, 16, v83
	v_and_b32_e32 v87, 0xffff0000, v83
	ds_write_b128 v118, v[32:35] offset:49680
	v_pk_mul_f32 v[32:33], v[42:43], v[58:59] op_sel_hi:[0,1]
	v_pk_mul_f32 v[34:35], v[42:43], v[62:63] op_sel_hi:[0,1]
	v_pk_mul_f32 v[80:81], v[42:43], v[84:85] op_sel_hi:[0,1]
	v_pk_mul_f32 v[42:43], v[42:43], v[86:87] op_sel_hi:[0,1]
	v_cvt_pk_bf16_f32 v32, v32, v33
	v_cvt_pk_bf16_f32 v33, v34, v35
	v_cvt_pk_bf16_f32 v34, v80, v81
	v_cvt_pk_bf16_f32 v35, v42, v43
	ds_write_b128 v118, v[32:35] offset:49696
	v_lshlrev_b32_e32 v32, 16, v76
	v_and_b32_e32 v33, 0xffff0000, v76
	v_lshlrev_b32_e32 v34, 16, v77
	v_and_b32_e32 v35, 0xffff0000, v77
	v_lshlrev_b32_e32 v42, 16, v72
	v_and_b32_e32 v43, 0xffff0000, v72
	v_lshlrev_b32_e32 v72, 16, v73
	v_and_b32_e32 v73, 0xffff0000, v73
	v_pk_mul_f32 v[32:33], v[40:41], v[32:33] op_sel_hi:[0,1]
	v_pk_mul_f32 v[34:35], v[40:41], v[34:35] op_sel_hi:[0,1]
	v_pk_mul_f32 v[42:43], v[40:41], v[42:43] op_sel_hi:[0,1]
	v_pk_mul_f32 v[72:73], v[40:41], v[72:73] op_sel_hi:[0,1]
	v_cvt_pk_bf16_f32 v32, v32, v33
	v_cvt_pk_bf16_f32 v33, v34, v35
	v_cvt_pk_bf16_f32 v34, v42, v43
	v_cvt_pk_bf16_f32 v35, v72, v73
	s_movk_i32 s18, 0x210
	ds_write_b128 v118, v[32:35] offset:58384
	v_lshlrev_b32_e32 v32, 16, v78
	v_and_b32_e32 v33, 0xffff0000, v78
	v_lshlrev_b32_e32 v34, 16, v79
	v_and_b32_e32 v35, 0xffff0000, v79
	v_lshlrev_b32_e32 v42, 16, v74
	v_and_b32_e32 v43, 0xffff0000, v74
	v_lshlrev_b32_e32 v72, 16, v75
	v_and_b32_e32 v73, 0xffff0000, v75
	v_mul_lo_u32 v88, v22, s18
	s_add_i32 s18, 0, 0x18420
	v_pk_mul_f32 v[32:33], v[40:41], v[32:33] op_sel_hi:[0,1]
	v_pk_mul_f32 v[34:35], v[40:41], v[34:35] op_sel_hi:[0,1]
	v_pk_mul_f32 v[42:43], v[40:41], v[42:43] op_sel_hi:[0,1]
	v_pk_mul_f32 v[40:41], v[40:41], v[72:73] op_sel_hi:[0,1]
	v_mul_u32_u24_e32 v90, 0x50, v27
	v_bfe_u32 v230, v167, 3, 1
	s_mov_b32 s42, 0xfdfe0606
	v_mul_lo_u32 v231, v230, s42
	v_add_u32_e32 v231, 0x5040100, v231
	v_mul_u32_u24_e32 v230, 0x4e, v230
	v_and_b32_e32 v127, -13, v22
	v_add3_u32 v89, s18, v88, v111
	v_cvt_pk_bf16_f32 v32, v32, v33
	v_cvt_pk_bf16_f32 v33, v34, v35
	v_cvt_pk_bf16_f32 v34, v42, v43
	v_cvt_pk_bf16_f32 v35, v40, v41
	s_add_i32 s18, 0, 0x10610
	v_lshlrev_b32_e32 v80, 1, v128
	ds_write_b128 v118, v[32:35] offset:58400
	v_add3_u32 v32, s18, v90, v80
	v_lshlrev_b32_e32 v81, 1, v127
	v_lshlrev_b32_e32 v82, 1, v129
	v_mul_f32_e32 v33, v117, v52
	v_add3_u32 v32, v32, v81, v82
	v_cvt_pk_bf16_f32 v33, v33, s0
	ds_write_b16 v32, v33
	v_mul_f32_e32 v33, v117, v53
	v_cvt_pk_bf16_f32 v33, v33, s0
	ds_write_b16 v32, v33 offset:80
	v_mul_f32_e32 v33, v117, v54
	v_cvt_pk_bf16_f32 v33, v33, s0
	ds_write_b16 v32, v33 offset:160
	v_mul_f32_e32 v33, v117, v55
	v_cvt_pk_bf16_f32 v33, v33, s0
	ds_write_b16 v32, v33 offset:240
	v_mul_f32_e32 v33, v117, v58
	v_cvt_pk_bf16_f32 v33, v33, s0
	ds_write_b16 v32, v33 offset:320
	v_mul_f32_e32 v33, v117, v59
	v_cvt_pk_bf16_f32 v33, v33, s0
	ds_write_b16 v32, v33 offset:400
	v_mul_f32_e32 v33, v117, v62
	v_cvt_pk_bf16_f32 v33, v33, s0
	ds_write_b16 v32, v33 offset:480
	v_mul_f32_e32 v33, v117, v63
	v_cvt_pk_bf16_f32 v33, v33, s0
	ds_write_b16 v32, v33 offset:560
	v_mul_f32_e32 v33, v117, v56
	v_cvt_pk_bf16_f32 v33, v33, s0
	ds_write_b16 v32, v33 offset:640
	v_mul_f32_e32 v33, v117, v57
	v_cvt_pk_bf16_f32 v33, v33, s0
	ds_write_b16 v32, v33 offset:720
	v_mul_f32_e32 v33, v117, v60
	v_cvt_pk_bf16_f32 v33, v33, s0
	ds_write_b16 v32, v33 offset:800
	v_mul_f32_e32 v33, v117, v61
	v_cvt_pk_bf16_f32 v33, v33, s0
	ds_write_b16 v32, v33 offset:880
	v_mul_f32_e32 v33, v117, v84
	v_cvt_pk_bf16_f32 v33, v33, s0
	ds_write_b16 v32, v33 offset:960
	v_mul_f32_e32 v33, v117, v85
	v_cvt_pk_bf16_f32 v33, v33, s0
	ds_write_b16 v32, v33 offset:1040
	v_mul_f32_e32 v33, v117, v86
	v_cvt_pk_bf16_f32 v33, v33, s0
	ds_write_b16 v32, v33 offset:1120
	v_mul_f32_e32 v33, v117, v87
	v_cvt_pk_bf16_f32 v33, v33, s0
	ds_write_b16 v32, v33 offset:1200
	s_add_i32 s18, 0, 0x14210
	v_lshlrev_b32_e32 v32, 16, v68
	v_and_b32_e32 v33, 0xffff0000, v68
	v_lshlrev_b32_e32 v34, 16, v69
	v_and_b32_e32 v35, 0xffff0000, v69
	v_add3_u32 v40, s18, v88, v111
	v_pk_mul_f32 v[32:33], v[110:111], v[32:33] op_sel_hi:[0,1]
	v_pk_mul_f32 v[34:35], v[110:111], v[34:35] op_sel_hi:[0,1]
	ds_write_b128 v40, v[32:35]
	v_lshlrev_b32_e32 v32, 16, v70
	v_and_b32_e32 v33, 0xffff0000, v70
	v_lshlrev_b32_e32 v34, 16, v71
	v_and_b32_e32 v35, 0xffff0000, v71
	v_pk_mul_f32 v[32:33], v[110:111], v[32:33] op_sel_hi:[0,1]
	v_pk_mul_f32 v[34:35], v[110:111], v[34:35] op_sel_hi:[0,1]
	ds_write_b128 v40, v[32:35] offset:16
	v_lshlrev_b32_e32 v32, 16, v64
	v_and_b32_e32 v33, 0xffff0000, v64
	v_lshlrev_b32_e32 v34, 16, v65
	v_and_b32_e32 v35, 0xffff0000, v65
	v_pk_mul_f32 v[32:33], v[110:111], v[32:33] op_sel_hi:[0,1]
	v_pk_mul_f32 v[34:35], v[110:111], v[34:35] op_sel_hi:[0,1]
	ds_write_b128 v40, v[32:35] offset:32
	v_lshlrev_b32_e32 v32, 16, v66
	v_and_b32_e32 v33, 0xffff0000, v66
	v_lshlrev_b32_e32 v34, 16, v67
	v_and_b32_e32 v35, 0xffff0000, v67
	v_pk_mul_f32 v[32:33], v[110:111], v[32:33] op_sel_hi:[0,1]
	v_pk_mul_f32 v[34:35], v[110:111], v[34:35] op_sel_hi:[0,1]
	ds_write_b128 v40, v[32:35] offset:48
	v_lshl_add_u64 v[32:33], v[20:21], 0, s[12:13]
	v_and_b32_e32 v20, 0x7f, v26
	v_lshlrev_b32_e32 v20, 4, v20
	v_lshl_add_u64 v[32:33], v[32:33], 0, v[20:21]
	v_lshl_add_u64 v[24:25], s[4:5], 0, v[24:25]
	v_add_lshl_u32 v20, s20, v27, 1
	v_lshl_add_u64 v[72:73], v[24:25], 0, v[20:21]
	v_and_b32_e32 v20, 7, v26
	s_waitcnt lgkmcnt(0)
	s_barrier
; __device__ __forceinline__ int opq(int x) { asm volatile("" : "+v"(x)); return x; }
; __device__ __forceinline__ unsigned char* karg_ws() { return *(volatile KAS ucptr_t*)((const KAS char*)__builtin_amdgcn_kernarg_segment_ptr() + 264); }
; #define INP(k) karg_in(k)
; #define tid opq((wave << 6) | lane_now())
; __device__ __forceinline__ void delta_rec_task(const Params& P, LAS unsigned char* lds, int b, int h, int tid) {
;     ...
;     if (producer) {
;         const int pt = opq(tid) - 256;
;         float dn16[16];
; #pragma unroll
;         for (int e = 0; e < 16; ++e) dn16[e] = INP(25)[(pt & 7) * 16 + e];
;         bf16* zgp = (bf16*)(karg_ws() + WS_Z + 5 * ZB) + ((size_t)b * SEQ + (pt >> 3)) * D + h * 128 + (pt & 7) * 16;
;         u32x4 zc0 = {0u, 0u, 0u, 0u}, zc1 = zc0, zn0, zn1;
;     ...
;         for (int c = 0; c < NC; ++c) {
;             if (c > 0) { dcur = dnxt; zc0 = zn0; zc1 = zn1; }
;             if (c + 2 < NC) delta_pre_load(b, h, c + 2, pt, dnxt);
;             zn0 = *(const u32x4*)(zgp + (size_t)c * 32 * D); zn1 = *(const u32x4*)(zgp + (size_t)c * 32 * D + 8);
	v_lshlrev_b64 v[74:75], 2, v[22:23]
	v_lshl_add_u64 v[22:23], v[24:25], 0, s[14:15]
	v_lshlrev_b32_e32 v20, 5, v20
	s_mov_b64 s[12:13], 0x1800
	v_lshl_add_u64 v[20:21], v[22:23], 0, v[20:21]
	v_lshl_add_u64 v[70:71], v[32:33], 0, s[12:13]
	s_lshl_b64 s[4:5], s[2:3], 13
	v_lshl_add_u64 v[76:77], s[16:17], 0, v[20:21]
	s_mov_b64 s[12:13], 0
	s_mov_b64 s[16:17], 0xb130000
	s_mov_b64 s[18:19], 0x3030000
	s_mov_b64 s[20:21], 0xd170000
	s_mov_b32 s3, 0xb130000
	s_mov_b32 s14, 0x3030000
	s_mov_b32 s34, 0xd170000
	s_mov_b32 s35, 0x2880000
	v_mov_b32_e32 v69, 0x2880000
	s_mov_b64 s[22:23], 0xf190000
	v_mov_b32_e32 v83, 0x358637bd
	s_mov_b64 s[24:25], 0x800
	s_mov_b32 s36, s15

; #define LAS __attribute__((address_space(3)))
; __device__ __forceinline__ unsigned f2bf(float f) { return pk2(f, f) & 0xffffu; }
; __device__ __forceinline__ void unpack8(const u32x4 u, float* x) { x[0] = bflo(u.x); x[1] = bfhi(u.x); x[2] = bflo(u.y); x[3] = bfhi(u.y); x[4] = bflo(u.z); x[5] = bfhi(u.z); x[6] = bflo(u.w); x[7] = bfhi(u.w); }
; __device__ __forceinline__ int perm16(int e) { return (e & ~12) | ((e >> 1) & 4) | ((e << 1) & 8); }
; __device__ __forceinline__ void delta_rec_stage(LAS unsigned char* buf, int pt, const DeltaPre& dp) {
;     const int tt = pt >> 3, dg = pt & 7, d0 = dg * 16;
;     { LAS bf16* dst = (LAS bf16*)(buf + (pt < 128 ? DR_TI : DR_AT)) + ((pt & 127) >> 2) * 40 + (pt & 3) * 8; *(LAS u32x4*)dst = dp.tia; }
;     if (pt == 0) *(LAS float*)(buf + DR_EGL) = __expf(dp.gl);
;     const float eg = __expf(dp.gct), ekd = __expf(dp.gl - dp.gct);
;     const float fq = dp.nq * eg, fkb = dp.nk * dp.bet * eg, fkd = dp.nk * ekd, bet = dp.bet;
;     float k[16], q[16], v[16];
;     unpack8(dp.k0, k); unpack8(dp.k1, k + 8); unpack8(dp.q0, q); unpack8(dp.q1, q + 8); unpack8(dp.v0, v); unpack8(dp.v1, v + 8);
;     LAS bf16* KB = (LAS bf16*)(buf + DR_KB) + tt * 136 + d0; LAS bf16* QD = (LAS bf16*)(buf + DR_QD) + tt * 136 + d0;
;     *(LAS bf16x8*)KB = pack8(k[0] * fkb, k[1] * fkb, k[2] * fkb, k[3] * fkb, k[8] * fkb, k[9] * fkb, k[10] * fkb, k[11] * fkb);
;     *(LAS bf16x8*)(KB + 8) = pack8(k[4] * fkb, k[5] * fkb, k[6] * fkb, k[7] * fkb, k[12] * fkb, k[13] * fkb, k[14] * fkb, k[15] * fkb);
;     *(LAS bf16x8*)QD = pack8(q[0] * fq, q[1] * fq, q[2] * fq, q[3] * fq, q[8] * fq, q[9] * fq, q[10] * fq, q[11] * fq);
;     *(LAS bf16x8*)(QD + 8) = pack8(q[4] * fq, q[5] * fq, q[6] * fq, q[7] * fq, q[12] * fq, q[13] * fq, q[14] * fq, q[15] * fq);
;     LAS bf16* KDT = (LAS bf16*)(buf + DR_KDT) + d0 * 40 + perm16(tt);
; #pragma unroll
;     for (int e = 0; e < 16; ++e) KDT[e * 40] = (bf16)f2bf(k[e] * fkd);
;     LAS float* VB = (LAS float*)(buf + DR_VB) + tt * 132 + d0;
; #pragma unroll
;     for (int e4 = 0; e4 < 4; ++e4) *(LAS f32x4*)(VB + 4 * e4) = (f32x4){v[4 * e4] * bet, v[4 * e4 + 1] * bet, v[4 * e4 + 2] * bet, v[4 * e4 + 3] * bet};
; }
.LBB0_1840:
	s_or_b64 exec, exec, s[26:27]
	v_mul_f32_e32 v110, 0x3fb8aa3b, v123
	v_exp_f32_e32 v117, v110
	v_sub_f32_e32 v110, v124, v123
	v_mul_f32_e32 v110, 0x3fb8aa3b, v110
	v_exp_f32_e32 v119, v110
	v_mul_f32_e32 v118, v116, v125
	v_mul_f32_e32 v118, v117, v118
	v_lshlrev_b32_e32 v128, 16, v48
	v_and_b32_e32 v129, 0xffff0000, v48
	v_lshlrev_b32_e32 v48, 16, v49
	v_and_b32_e32 v49, 0xffff0000, v49
	v_lshlrev_b32_e32 v130, 16, v44
	v_and_b32_e32 v131, 0xffff0000, v44
	v_lshlrev_b32_e32 v134, 16, v45
	v_and_b32_e32 v135, 0xffff0000, v45
	v_mul_f32_e32 v110, v117, v126
	v_mul_f32_e32 v117, v125, v119
	v_pk_mul_f32 v[124:125], v[118:119], v[128:129] op_sel_hi:[0,1]
	v_pk_mul_f32 v[126:127], v[118:119], v[48:49] op_sel_hi:[0,1]
	v_pk_mul_f32 v[132:133], v[118:119], v[130:131] op_sel_hi:[0,1]
	v_pk_mul_f32 v[44:45], v[118:119], v[134:135] op_sel_hi:[0,1]
	v_add3_u32 v120, s37, v91, v114
	v_cvt_pk_bf16_f32 v124, v124, v125
	v_cvt_pk_bf16_f32 v125, v126, v127
	v_cvt_pk_bf16_f32 v126, v132, v133
	v_cvt_pk_bf16_f32 v127, v44, v45
	ds_write_b128 v120, v[124:127]
	v_lshlrev_b32_e32 v124, 16, v50
	v_and_b32_e32 v125, 0xffff0000, v50
	v_lshlrev_b32_e32 v50, 16, v51
	v_and_b32_e32 v51, 0xffff0000, v51
	v_lshlrev_b32_e32 v132, 16, v46
	v_and_b32_e32 v133, 0xffff0000, v46
	v_lshlrev_b32_e32 v138, 16, v47
	v_and_b32_e32 v139, 0xffff0000, v47
	v_pk_mul_f32 v[44:45], v[118:119], v[124:125] op_sel_hi:[0,1]
	v_pk_mul_f32 v[126:127], v[118:119], v[50:51] op_sel_hi:[0,1]
	v_pk_mul_f32 v[136:137], v[118:119], v[132:133] op_sel_hi:[0,1]
	v_pk_mul_f32 v[118:119], v[118:119], v[138:139] op_sel_hi:[0,1]
	v_cvt_pk_bf16_f32 v44, v44, v45
	v_cvt_pk_bf16_f32 v45, v126, v127
	v_cvt_pk_bf16_f32 v46, v136, v137
	v_cvt_pk_bf16_f32 v47, v118, v119
	ds_write_b128 v120, v[44:47] offset:16
	v_lshlrev_b32_e32 v44, 16, v36
	v_and_b32_e32 v45, 0xffff0000, v36
	v_lshlrev_b32_e32 v36, 16, v37
	v_and_b32_e32 v37, 0xffff0000, v37
	v_lshlrev_b32_e32 v46, 16, v28
	v_and_b32_e32 v47, 0xffff0000, v28
	v_lshlrev_b32_e32 v28, 16, v29
	v_and_b32_e32 v29, 0xffff0000, v29
	v_pk_mul_f32 v[44:45], v[110:111], v[44:45] op_sel_hi:[0,1]
	v_pk_mul_f32 v[36:37], v[110:111], v[36:37] op_sel_hi:[0,1]
	v_pk_mul_f32 v[46:47], v[110:111], v[46:47] op_sel_hi:[0,1]
	v_pk_mul_f32 v[28:29], v[110:111], v[28:29] op_sel_hi:[0,1]
	v_cvt_pk_bf16_f32 v44, v44, v45
	v_cvt_pk_bf16_f32 v45, v36, v37
	v_cvt_pk_bf16_f32 v46, v46, v47
	v_cvt_pk_bf16_f32 v47, v28, v29
	v_lshlrev_b32_e32 v28, 16, v38
	v_and_b32_e32 v29, 0xffff0000, v38
	v_lshlrev_b32_e32 v36, 16, v39
	v_and_b32_e32 v37, 0xffff0000, v39
	v_lshlrev_b32_e32 v38, 16, v30
	v_and_b32_e32 v39, 0xffff0000, v30
	v_lshlrev_b32_e32 v30, 16, v31
	v_and_b32_e32 v31, 0xffff0000, v31
	ds_write_b128 v120, v[44:47] offset:8704
	v_pk_mul_f32 v[28:29], v[110:111], v[28:29] op_sel_hi:[0,1]
	v_pk_mul_f32 v[36:37], v[110:111], v[36:37] op_sel_hi:[0,1]
	v_pk_mul_f32 v[38:39], v[110:111], v[38:39] op_sel_hi:[0,1]
	v_pk_mul_f32 v[44:45], v[110:111], v[30:31] op_sel_hi:[0,1]
	v_cvt_pk_bf16_f32 v28, v28, v29
	v_cvt_pk_bf16_f32 v29, v36, v37
	v_cvt_pk_bf16_f32 v30, v38, v39
	v_cvt_pk_bf16_f32 v31, v44, v45
	ds_write_b128 v120, v[28:31] offset:8720
	v_add3_u32 v28, s37, v90, v80
	v_add3_u32 v28, v28, v81, v82
	v_add_u32_e32 v232, v28, v230
	v_pk_mul_f32 v[190:191], v[116:117], v[128:129] op_sel:[1,0]
	v_pk_mul_f32 v[192:193], v[116:117], v[48:49] op_sel:[1,0]
	v_pk_mul_f32 v[194:195], v[116:117], v[124:125] op_sel:[1,0]
	v_pk_mul_f32 v[196:197], v[116:117], v[50:51] op_sel:[1,0]
	v_pk_mul_f32 v[198:199], v[116:117], v[130:131] op_sel:[1,0]
	v_pk_mul_f32 v[200:201], v[116:117], v[134:135] op_sel:[1,0]
	v_pk_mul_f32 v[202:203], v[116:117], v[132:133] op_sel:[1,0]
	v_pk_mul_f32 v[204:205], v[116:117], v[138:139] op_sel:[1,0]
	v_cvt_pk_bf16_f32 v206, v190, v191
	v_cvt_pk_bf16_f32 v207, v192, v193
	v_cvt_pk_bf16_f32 v208, v194, v195
	v_cvt_pk_bf16_f32 v209, v196, v197
	v_cvt_pk_bf16_f32 v210, v198, v199
	v_cvt_pk_bf16_f32 v211, v200, v201
	v_cvt_pk_bf16_f32 v212, v202, v203
	v_cvt_pk_bf16_f32 v213, v204, v205
	v_mov_b32_dpp v214, v206 row_ror:8 row_mask:0xf bank_mask:0xf
	v_mov_b32_dpp v215, v207 row_ror:8 row_mask:0xf bank_mask:0xf
	v_mov_b32_dpp v216, v208 row_ror:8 row_mask:0xf bank_mask:0xf
	v_mov_b32_dpp v217, v209 row_ror:8 row_mask:0xf bank_mask:0xf
	v_mov_b32_dpp v218, v210 row_ror:8 row_mask:0xf bank_mask:0xf
	v_mov_b32_dpp v219, v211 row_ror:8 row_mask:0xf bank_mask:0xf
	v_mov_b32_dpp v220, v212 row_ror:8 row_mask:0xf bank_mask:0xf
	v_mov_b32_dpp v221, v213 row_ror:8 row_mask:0xf bank_mask:0xf
	v_perm_b32 v190, v214, v206, v231
	v_perm_b32 v191, v215, v207, v231
	v_perm_b32 v192, v216, v208, v231
	v_perm_b32 v193, v217, v209, v231
	v_perm_b32 v194, v218, v210, v231
	v_perm_b32 v195, v219, v211, v231
	v_perm_b32 v196, v220, v212, v231
	v_perm_b32 v197, v221, v213, v231
	ds_write_b32 v232, v190 offset:17408
	ds_write_b32 v232, v191 offset:17568
	ds_write_b32 v232, v192 offset:17728
	ds_write_b32 v232, v193 offset:17888
	ds_write_b32 v232, v194 offset:18048
	ds_write_b32 v232, v195 offset:18208
	ds_write_b32 v232, v196 offset:18368
	ds_write_b32 v232, v197 offset:18528
	v_lshlrev_b32_e32 v28, 16, v16
	v_and_b32_e32 v29, 0xffff0000, v16
	v_lshlrev_b32_e32 v16, 16, v17
	v_and_b32_e32 v17, 0xffff0000, v17
	v_pk_mul_f32 v[30:31], v[116:117], v[16:17] op_sel_hi:[0,1]
	v_lshlrev_b32_e32 v16, 16, v18
	v_and_b32_e32 v17, 0xffff0000, v18
	v_lshlrev_b32_e32 v18, 16, v19
	v_and_b32_e32 v19, 0xffff0000, v19
	v_add3_u32 v110, s37, v88, v111
	v_pk_mul_f32 v[16:17], v[116:117], v[16:17] op_sel_hi:[0,1]
	v_pk_mul_f32 v[18:19], v[116:117], v[18:19] op_sel_hi:[0,1]
	s_and_b32 s26, s15, 32
	ds_write_b128 v110, v[16:19] offset:32784
	v_lshlrev_b32_e32 v16, 16, v12
	v_and_b32_e32 v17, 0xffff0000, v12
	v_lshlrev_b32_e32 v12, 16, v13
	v_and_b32_e32 v13, 0xffff0000, v13
	s_mulk_i32 s26, 0x210
	v_pk_mul_f32 v[16:17], v[116:117], v[16:17] op_sel_hi:[0,1]
	v_pk_mul_f32 v[18:19], v[116:117], v[12:13] op_sel_hi:[0,1]
	v_add_u32_e32 v44, s26, v89
	ds_write_b128 v110, v[16:19] offset:32800
	ds_read_b128 v[16:19], v44
	v_pk_mul_f32 v[28:29], v[116:117], v[28:29] op_sel_hi:[0,1]
	ds_write_b128 v110, v[28:31] offset:32768
	ds_read_b128 v[28:31], v44 offset:16
	ds_read_b128 v[36:39], v44 offset:32
	ds_read_b128 v[44:47], v44 offset:48
	v_lshlrev_b32_e32 v12, 16, v14
	s_waitcnt lgkmcnt(4)
; #define LAS __attribute__((address_space(3)))
; __device__ __forceinline__ float rsq_f(float x) { return __builtin_amdgcn_rsqf(x); }
; __device__ __forceinline__ float red8(float x) { x += dpp_f<0xB1>(x); x += dpp_f<0x4E>(x); x += dpp_f<0x141>(x); return x; }
; __device__ __forceinline__ void unpack8(const u32x4 u, float* x) { x[0] = bflo(u.x); x[1] = bfhi(u.x); x[2] = bflo(u.y); x[3] = bfhi(u.y); x[4] = bflo(u.z); x[5] = bfhi(u.z); x[6] = bflo(u.w); x[7] = bfhi(u.w); }
; #define DR_BAR() do { asm volatile("s_waitcnt lgkmcnt(0)" ::: "memory"); __builtin_amdgcn_s_barrier(); asm volatile("" ::: "memory"); } while (0)
; __device__ __forceinline__ void delta_out_norm(const LAS float* ob, int pt, const float* dn16, const u32x4 z0, const u32x4 z1, bf16* dst) {
;     const LAS float* p = ob + (pt >> 3) * 132 + (pt & 7) * 16;
;     float o[16], z[16];
; #pragma unroll
;     for (int e4 = 0; e4 < 4; ++e4) { const f32x4 t = *(const LAS f32x4*)(p + 4 * e4); o[4 * e4] = t[0]; o[4 * e4 + 1] = t[1]; o[4 * e4 + 2] = t[2]; o[4 * e4 + 3] = t[3]; }
;     float ss = 0.f;
; #pragma unroll
;     for (int e = 0; e < 16; ++e) ss += o[e] * o[e];
;     ss = red8(ss);
;     const float rstd = rsq_f(ss * (1.f / 128.f) + EPS);
;     unpack8(z0, z); unpack8(z1, z + 8);
; #pragma unroll
;     for (int e = 0; e < 16; ++e) o[e] = o[e] * rstd * dn16[e] * z[e];
;     *(bf16x8*)dst = pack8(o[0], o[1], o[2], o[3], o[4], o[5], o[6], o[7]); *(bf16x8*)(dst + 8) = pack8(o[8], o[9], o[10], o[11], o[12], o[13], o[14], o[15]);
; }
; __device__ __forceinline__ void delta_rec_task(const Params& P, LAS unsigned char* lds, int b, int h, int tid) {
;     ...
;         for (int c = 0; c < NC; ++c) {
;             if (c > 0) { dcur = dnxt; zc0 = zn0; zc1 = zn1; }
;             if (c + 2 < NC) delta_pre_load(b, h, c + 2, pt, dnxt);
;             zn0 = *(const u32x4*)(zgp + (size_t)c * 32 * D); zn1 = *(const u32x4*)(zgp + (size_t)c * 32 * D + 8);
;             if (c + 1 < NC) delta_rec_stage(lds + ((c + 1) & 1) * DR_BUF, pt, dcur);
;             if (c > 0) delta_out_norm((const LAS float*)(lds + DR_OB) + ((c - 1) & 1) * 32 * 132, pt, dn16, zc0, zc1, zgp + (size_t)(c - 1) * 32 * D);
;             DR_BAR();
;         }
	v_mul_f32_e32 v50, v17, v17
	v_fmac_f32_e32 v50, v16, v16
	v_fmac_f32_e32 v50, v18, v18
	v_fmac_f32_e32 v50, v19, v19
	s_waitcnt lgkmcnt(2)
	v_fmac_f32_e32 v50, v28, v28
	v_fmac_f32_e32 v50, v29, v29
	v_fmac_f32_e32 v50, v30, v30
	v_fmac_f32_e32 v50, v31, v31
	s_waitcnt lgkmcnt(1)
	v_fmac_f32_e32 v50, v36, v36
	v_fmac_f32_e32 v50, v37, v37
	v_pk_mul_f32 v[48:49], v[38:39], v[38:39]
	v_and_b32_e32 v13, 0xffff0000, v14
	v_lshlrev_b32_e32 v14, 16, v15
	v_and_b32_e32 v15, 0xffff0000, v15
	v_add_f32_e32 v48, v48, v50
	v_pk_mul_f32 v[12:13], v[116:117], v[12:13] op_sel_hi:[0,1]
	v_pk_mul_f32 v[14:15], v[116:117], v[14:15] op_sel_hi:[0,1]
	v_add_f32_e32 v116, v49, v48
	s_waitcnt lgkmcnt(0)
	v_pk_mul_f32 v[50:51], v[44:45], v[44:45]
	v_pk_mul_f32 v[48:49], v[46:47], v[46:47]
	v_add_f32_e32 v50, v50, v116
	v_add_f32_e32 v50, v51, v50
	v_add_f32_e32 v48, v48, v50
	v_add_f32_e32 v48, v49, v48
	ds_write_b128 v110, v[12:15] offset:32816
	s_waitcnt vmcnt(15)
	v_lshlrev_b32_e32 v12, 16, v8
	v_add_f32_dpp v48, v48, v48 quad_perm:[1,0,3,2] row_mask:0xf bank_mask:0xf bound_ctrl:1
	v_and_b32_e32 v13, 0xffff0000, v8
	v_lshlrev_b32_e32 v8, 16, v9
	v_add_f32_dpp v48, v48, v48 quad_perm:[2,3,0,1] row_mask:0xf bank_mask:0xf bound_ctrl:1
	v_and_b32_e32 v9, 0xffff0000, v9
	s_add_i32 s36, s36, 1
	v_add_f32_dpp v48, v48, v48 row_half_mirror row_mask:0xf bank_mask:0xf bound_ctrl:1
	v_fmamk_f32 v48, v48, 0x3c000000, v83
	v_rsq_f32_e32 v48, v48
	s_add_u32 s12, s12, 0x10000
	s_addc_u32 s13, s13, 0
	s_add_u32 s4, s4, 0x80
	v_pk_mul_f32 v[14:15], v[16:17], v[48:49] op_sel_hi:[1,0]
	v_pk_mul_f32 v[16:17], v[28:29], v[48:49] op_sel_hi:[1,0]
	v_pk_mul_f32 v[14:15], v[102:103], v[14:15]
	v_pk_mul_f32 v[16:17], v[98:99], v[16:17]
	v_pk_mul_f32 v[12:13], v[14:15], v[12:13]
	v_pk_mul_f32 v[14:15], v[18:19], v[48:49] op_sel_hi:[1,0]
	v_pk_mul_f32 v[18:19], v[36:37], v[48:49] op_sel_hi:[1,0]
	v_pk_mul_f32 v[14:15], v[100:101], v[14:15]
	v_pk_mul_f32 v[18:19], v[94:95], v[18:19]
	v_pk_mul_f32 v[8:9], v[14:15], v[8:9]
	v_lshlrev_b32_e32 v14, 16, v10
	v_and_b32_e32 v15, 0xffff0000, v10
	v_pk_mul_f32 v[14:15], v[16:17], v[14:15]
	v_pk_mul_f32 v[16:17], v[30:31], v[48:49] op_sel_hi:[1,0]
	v_lshlrev_b32_e32 v10, 16, v11
	v_and_b32_e32 v11, 0xffff0000, v11
	v_pk_mul_f32 v[16:17], v[96:97], v[16:17]
	v_pk_mul_f32 v[28:29], v[44:45], v[48:49] op_sel_hi:[1,0]
	v_pk_mul_f32 v[10:11], v[16:17], v[10:11]
	s_waitcnt vmcnt(14)
	v_lshlrev_b32_e32 v16, 16, v4
	v_and_b32_e32 v17, 0xffff0000, v4
	v_pk_mul_f32 v[16:17], v[18:19], v[16:17]
	v_pk_mul_f32 v[18:19], v[38:39], v[48:49] op_sel_hi:[1,0]
	v_lshlrev_b32_e32 v4, 16, v5
	v_and_b32_e32 v5, 0xffff0000, v5
	v_pk_mul_f32 v[18:19], v[92:93], v[18:19]
	v_pk_mul_f32 v[28:29], v[104:105], v[28:29]
	v_pk_mul_f32 v[18:19], v[18:19], v[4:5]
	v_lshlrev_b32_e32 v4, 16, v6
	v_and_b32_e32 v5, 0xffff0000, v6
	v_pk_mul_f32 v[28:29], v[28:29], v[4:5]
	v_lshlrev_b32_e32 v4, 16, v7
	v_and_b32_e32 v5, 0xffff0000, v7
	v_pk_mul_f32 v[6:7], v[46:47], v[48:49] op_sel_hi:[1,0]
	s_addc_u32 s5, s5, 0
	v_pk_mul_f32 v[6:7], v[106:107], v[6:7]
	s_add_i32 s15, s15, 32
	v_pk_mul_f32 v[30:31], v[6:7], v[4:5]
	v_cvt_pk_bf16_f32 v5, v8, v9
	v_add_co_u32_e32 v8, vcc, s31, v78
	v_cvt_pk_bf16_f32 v4, v12, v13
	v_cvt_pk_bf16_f32 v6, v14, v15
	v_cvt_pk_bf16_f32 v7, v10, v11
	v_addc_co_u32_e32 v9, vcc, 0, v79, vcc
	global_store_dwordx4 v[8:9], v[4:7], off
	s_cmp_eq_u32 s12, 0x3d0000
	v_lshl_add_u64 v[70:71], v[70:71], 0, s[24:25]
	v_cvt_pk_bf16_f32 v4, v16, v17
	v_cvt_pk_bf16_f32 v5, v18, v19
	v_cvt_pk_bf16_f32 v6, v28, v29
	v_cvt_pk_bf16_f32 v7, v30, v31
	global_store_dwordx4 v[8:9], v[4:7], off offset:16
	s_waitcnt lgkmcnt(0)
	s_barrier
	s_cbranch_scc1 .LBB0_1842
	s_waitcnt vmcnt(3)
	v_mov_b64_e32 v[8:9], v[24:25]
	s_waitcnt vmcnt(2)
	v_mov_b64_e32 v[4:5], v[20:21]
	v_mov_b64_e32 v[48:49], v[64:65]
	v_mov_b64_e32 v[44:45], v[60:61]
	v_mov_b64_e32 v[36:37], v[56:57]
	v_mov_b64_e32 v[28:29], v[52:53]
	v_mov_b64_e32 v[16:17], v[40:41]
	v_mov_b64_e32 v[12:13], v[32:33]
	v_mov_b64_e32 v[10:11], v[26:27]
	v_mov_b64_e32 v[6:7], v[22:23]
	v_mov_b64_e32 v[50:51], v[66:67]
	v_mov_b64_e32 v[46:47], v[62:63]
	v_mov_b64_e32 v[38:39], v[58:59]
	v_mov_b64_e32 v[30:31], v[54:55]
	v_mov_b64_e32 v[18:19], v[42:43]
	v_mov_b64_e32 v[14:15], v[34:35]
	v_mov_b32_e32 v123, v84
	v_mov_b32_e32 v124, v85
	v_mov_b32_e32 v116, v68
	v_mov_b32_e32 v125, v86
	v_mov_b32_e32 v126, v87
	s_branch .LBB0_1838
